# v45 + memory-attention unit epilogues (layers 2-3): 8-byte row stores paired into 16-byte stores via v_permlane32_swap
# baseline (speedup 1.0000x reference)
.LBB0_1592:
	s_lshl_b32 s0, s0, 1
	s_add_u32 s0, s86, s0
	s_addc_u32 s1, s87, 0
	s_setprio 0
	ds_bpermute_b32 v4, v151, v153
	v_lshl_add_u64 v[2:3], s[0:1], 0, v[114:115]
	v_lshlrev_b32_e32 v0, 4, v150
	v_lshl_add_u64 v[2:3], v[2:3], 0, v[0:1]
	s_mov_b64 s[4:5], 0
	s_waitcnt lgkmcnt(0)
	v_add_f32_e32 v4, v153, v4
	v_div_scale_f32 v5, s[0:1], v4, v4, 1.0
	v_rcp_f32_e32 v6, v5
	v_div_scale_f32 v0, vcc, 1.0, v4, 1.0
	v_fma_f32 v7, -v5, v6, 1.0
	v_fmac_f32_e32 v6, v7, v6
	v_mul_f32_e32 v7, v0, v6
	v_fma_f32 v8, -v5, v7, v0
	v_fmac_f32_e32 v7, v8, v6
	v_fma_f32 v0, -v5, v7, v0
	v_div_fmas_f32 v0, v0, v6, v7
	v_div_fixup_f32 v0, v0, v4, 1.0
	v_pk_mul_f32 v[4:5], v[50:51], v[0:1] op_sel_hi:[1,0]
	v_pk_mul_f32 v[6:7], v[52:53], v[0:1] op_sel_hi:[1,0]
	v_cvt_pk_bf16_f32 v4, v4, v5
	v_cvt_pk_bf16_f32 v5, v6, v7
	v_mov_b32_e32 v236, v4
	v_mov_b32_e32 v237, v5
	s_nop 1
	v_pk_mul_f32 v[4:5], v[54:55], v[0:1] op_sel_hi:[1,0]
	v_pk_mul_f32 v[6:7], v[56:57], v[0:1] op_sel_hi:[1,0]
	v_cvt_pk_bf16_f32 v4, v4, v5
	v_cvt_pk_bf16_f32 v5, v6, v7
	v_lshl_add_u64 v[6:7], v[2:3], 0, 16
	v_mov_b32_e32 v238, v4
	v_mov_b32_e32 v239, v5
	s_nop 1
	v_permlane32_swap_b32_e32 v236, v238
	v_permlane32_swap_b32_e32 v237, v239
	global_store_dwordx4 v[6:7], v[236:239], off offset:-16 sc1
	s_nop 1
	v_pk_mul_f32 v[4:5], v[58:59], v[0:1] op_sel_hi:[1,0]
	v_pk_mul_f32 v[6:7], v[60:61], v[0:1] op_sel_hi:[1,0]
	v_cvt_pk_bf16_f32 v4, v4, v5
	v_cvt_pk_bf16_f32 v5, v6, v7
	v_lshl_add_u64 v[6:7], v[2:3], 0, 32
	v_mov_b32_e32 v236, v4
	v_mov_b32_e32 v237, v5
	s_nop 1
	v_pk_mul_f32 v[4:5], v[62:63], v[0:1] op_sel_hi:[1,0]
	v_pk_mul_f32 v[6:7], v[64:65], v[0:1] op_sel_hi:[1,0]
	v_cvt_pk_bf16_f32 v4, v4, v5
	v_cvt_pk_bf16_f32 v5, v6, v7
	v_lshl_add_u64 v[6:7], v[2:3], 0, 48
	v_mov_b32_e32 v238, v4
	v_mov_b32_e32 v239, v5
	s_nop 1
	v_permlane32_swap_b32_e32 v236, v238
	v_permlane32_swap_b32_e32 v237, v239
	global_store_dwordx4 v[6:7], v[236:239], off offset:-16 sc1
	s_nop 1
	v_pk_mul_f32 v[4:5], v[34:35], v[0:1] op_sel_hi:[1,0]
	v_pk_mul_f32 v[6:7], v[36:37], v[0:1] op_sel_hi:[1,0]
	v_cvt_pk_bf16_f32 v4, v4, v5
	v_cvt_pk_bf16_f32 v5, v6, v7
	v_lshl_add_u64 v[6:7], v[2:3], 0, 64
	v_mov_b32_e32 v236, v4
	v_mov_b32_e32 v237, v5
	s_nop 1
	v_pk_mul_f32 v[4:5], v[38:39], v[0:1] op_sel_hi:[1,0]
	v_pk_mul_f32 v[6:7], v[40:41], v[0:1] op_sel_hi:[1,0]
	v_cvt_pk_bf16_f32 v4, v4, v5
	v_cvt_pk_bf16_f32 v5, v6, v7
	v_lshl_add_u64 v[6:7], v[2:3], 0, s[42:43]
	v_mov_b32_e32 v238, v4
	v_mov_b32_e32 v239, v5
	s_nop 1
	v_permlane32_swap_b32_e32 v236, v238
	v_permlane32_swap_b32_e32 v237, v239
	global_store_dwordx4 v[6:7], v[236:239], off offset:-16 sc1
	s_nop 1
	v_pk_mul_f32 v[4:5], v[42:43], v[0:1] op_sel_hi:[1,0]
	v_pk_mul_f32 v[6:7], v[44:45], v[0:1] op_sel_hi:[1,0]
	v_cvt_pk_bf16_f32 v4, v4, v5
	v_cvt_pk_bf16_f32 v5, v6, v7
	v_lshl_add_u64 v[6:7], v[2:3], 0, s[44:45]
	v_mov_b32_e32 v236, v4
	v_mov_b32_e32 v237, v5
	s_nop 1
	v_pk_mul_f32 v[4:5], v[46:47], v[0:1] op_sel_hi:[1,0]
	v_pk_mul_f32 v[6:7], v[48:49], v[0:1] op_sel_hi:[1,0]
	v_cvt_pk_bf16_f32 v4, v4, v5
	v_cvt_pk_bf16_f32 v5, v6, v7
	v_lshl_add_u64 v[2:3], v[2:3], 0, s[52:53]
	v_mov_b32_e32 v238, v4
	v_mov_b32_e32 v239, v5
	s_nop 1
	v_permlane32_swap_b32_e32 v236, v238
	v_permlane32_swap_b32_e32 v237, v239
	global_store_dwordx4 v[2:3], v[236:239], off offset:-16 sc1
	s_nop 1

.LBB0_2145:
	s_lshl_b32 s0, s0, 1
	s_add_u32 s0, s86, s0
	s_addc_u32 s1, s87, 0
	s_setprio 0
	ds_bpermute_b32 v4, v151, v153
	v_lshl_add_u64 v[2:3], s[0:1], 0, v[114:115]
	v_lshlrev_b32_e32 v0, 4, v150
	v_lshl_add_u64 v[2:3], v[2:3], 0, v[0:1]
	s_mov_b64 s[4:5], 0
	s_waitcnt lgkmcnt(0)
	v_add_f32_e32 v4, v153, v4
	v_div_scale_f32 v5, s[0:1], v4, v4, 1.0
	v_rcp_f32_e32 v6, v5
	v_div_scale_f32 v0, vcc, 1.0, v4, 1.0
	v_fma_f32 v7, -v5, v6, 1.0
	v_fmac_f32_e32 v6, v7, v6
	v_mul_f32_e32 v7, v0, v6
	v_fma_f32 v8, -v5, v7, v0
	v_fmac_f32_e32 v7, v8, v6
	v_fma_f32 v0, -v5, v7, v0
	v_div_fmas_f32 v0, v0, v6, v7
	v_div_fixup_f32 v0, v0, v4, 1.0
	v_pk_mul_f32 v[4:5], v[50:51], v[0:1] op_sel_hi:[1,0]
	v_pk_mul_f32 v[6:7], v[52:53], v[0:1] op_sel_hi:[1,0]
	v_cvt_pk_bf16_f32 v4, v4, v5
	v_cvt_pk_bf16_f32 v5, v6, v7
	v_mov_b32_e32 v236, v4
	v_mov_b32_e32 v237, v5
	s_nop 1
	v_pk_mul_f32 v[4:5], v[54:55], v[0:1] op_sel_hi:[1,0]
	v_pk_mul_f32 v[6:7], v[56:57], v[0:1] op_sel_hi:[1,0]
	v_cvt_pk_bf16_f32 v4, v4, v5
	v_cvt_pk_bf16_f32 v5, v6, v7
	v_lshl_add_u64 v[6:7], v[2:3], 0, 16
	v_mov_b32_e32 v238, v4
	v_mov_b32_e32 v239, v5
	s_nop 1
	v_permlane32_swap_b32_e32 v236, v238
	v_permlane32_swap_b32_e32 v237, v239
	global_store_dwordx4 v[6:7], v[236:239], off offset:-16 sc1
	s_nop 1
	v_pk_mul_f32 v[4:5], v[58:59], v[0:1] op_sel_hi:[1,0]
	v_pk_mul_f32 v[6:7], v[60:61], v[0:1] op_sel_hi:[1,0]
	v_cvt_pk_bf16_f32 v4, v4, v5
	v_cvt_pk_bf16_f32 v5, v6, v7
	v_lshl_add_u64 v[6:7], v[2:3], 0, 32
	v_mov_b32_e32 v236, v4
	v_mov_b32_e32 v237, v5
	s_nop 1
	v_pk_mul_f32 v[4:5], v[62:63], v[0:1] op_sel_hi:[1,0]
	v_pk_mul_f32 v[6:7], v[64:65], v[0:1] op_sel_hi:[1,0]
	v_cvt_pk_bf16_f32 v4, v4, v5
	v_cvt_pk_bf16_f32 v5, v6, v7
	v_lshl_add_u64 v[6:7], v[2:3], 0, 48
	v_mov_b32_e32 v238, v4
	v_mov_b32_e32 v239, v5
	s_nop 1
	v_permlane32_swap_b32_e32 v236, v238
	v_permlane32_swap_b32_e32 v237, v239
	global_store_dwordx4 v[6:7], v[236:239], off offset:-16 sc1
	s_nop 1
	v_pk_mul_f32 v[4:5], v[34:35], v[0:1] op_sel_hi:[1,0]
	v_pk_mul_f32 v[6:7], v[36:37], v[0:1] op_sel_hi:[1,0]
	v_cvt_pk_bf16_f32 v4, v4, v5
	v_cvt_pk_bf16_f32 v5, v6, v7
	v_lshl_add_u64 v[6:7], v[2:3], 0, 64
	v_mov_b32_e32 v236, v4
	v_mov_b32_e32 v237, v5
	s_nop 1
	v_pk_mul_f32 v[4:5], v[38:39], v[0:1] op_sel_hi:[1,0]
	v_pk_mul_f32 v[6:7], v[40:41], v[0:1] op_sel_hi:[1,0]
	v_cvt_pk_bf16_f32 v4, v4, v5
	v_cvt_pk_bf16_f32 v5, v6, v7
	v_lshl_add_u64 v[6:7], v[2:3], 0, s[28:29]
	v_mov_b32_e32 v238, v4
	v_mov_b32_e32 v239, v5
	s_nop 1
	v_permlane32_swap_b32_e32 v236, v238
	v_permlane32_swap_b32_e32 v237, v239
	global_store_dwordx4 v[6:7], v[236:239], off offset:-16 sc1
	s_nop 1
	v_pk_mul_f32 v[4:5], v[42:43], v[0:1] op_sel_hi:[1,0]
	v_pk_mul_f32 v[6:7], v[44:45], v[0:1] op_sel_hi:[1,0]
	v_cvt_pk_bf16_f32 v4, v4, v5
	v_cvt_pk_bf16_f32 v5, v6, v7
	v_lshl_add_u64 v[6:7], v[2:3], 0, s[36:37]
	v_mov_b32_e32 v236, v4
	v_mov_b32_e32 v237, v5
	s_nop 1
	v_pk_mul_f32 v[4:5], v[46:47], v[0:1] op_sel_hi:[1,0]
	v_pk_mul_f32 v[6:7], v[48:49], v[0:1] op_sel_hi:[1,0]
	v_cvt_pk_bf16_f32 v4, v4, v5
	v_cvt_pk_bf16_f32 v5, v6, v7
	v_lshl_add_u64 v[2:3], v[2:3], 0, s[40:41]
	v_mov_b32_e32 v238, v4
	v_mov_b32_e32 v239, v5
	s_nop 1
	v_permlane32_swap_b32_e32 v236, v238
	v_permlane32_swap_b32_e32 v237, v239
	global_store_dwordx4 v[2:3], v[236:239], off offset:-16 sc1
	s_nop 1
